# GEMM main loops: s_setprio 1 for the load-issuing wave during its load segment (LDS reads + LDS-DMA issue), back to 0 before the segment's waits
# speedup vs baseline: 1.0159x; 1.0002x over previous
.LBB0_630:
	s_ashr_i32 s85, s84, 31
	s_lshl_b64 s[22:23], s[84:85], 20
	s_cmp_eq_u32 s52, 0
	v_mov_b64_e32 v[0:1], 0x3a0
	s_cselect_b32 s31, s14, s50
	v_cmp_lt_i64_e32 vcc, s[76:77], v[0:1]
	s_cselect_b32 s30, s15, s51
	s_cselect_b32 s38, s8, s14
	s_cselect_b32 s39, s9, s15
	s_add_u32 s76, s31, s22
	s_addc_u32 s77, s30, s23
	s_and_b64 s[22:23], vcc, exec
	s_cselect_b32 s30, s77, s89
	s_cselect_b32 s31, s76, s88
	s_ashr_i32 s83, s82, 31
	s_lshl_b64 s[22:23], s[82:83], 20
	s_add_u32 s86, s38, s22
	s_addc_u32 s87, s39, s23
	s_and_b64 s[22:23], vcc, exec
	s_cselect_b32 s38, s87, s91
	s_cselect_b32 s39, s86, s90
	s_add_u32 s88, s88, 0x80080
	s_addc_u32 s89, s89, 0
	s_add_u32 s41, s90, 0x100
	s_addc_u32 s42, s91, 0
	s_mov_b32 s43, -2
	s_add_u32 s22, s88, 0xfff80080
	s_addc_u32 s23, s89, -1
	s_add_u32 s44, s88, 0xfff80000
	s_addc_u32 s45, s89, -1
	s_cmp_eq_u32 s43, 28
	s_cselect_b32 s23, s30, s23
	s_cselect_b32 s22, s31, s22
	s_cselect_b32 s91, s38, s42
	s_cselect_b32 s90, s39, s41
	s_add_i32 s81, 0, 0x14000
	s_setprio 1
	ds_read_b128 v[144:147], v222
	ds_read_b128 v[148:151], v222 offset:1024
	ds_read_b128 v[152:155], v222 offset:2048
	ds_read_b128 v[156:159], v222 offset:3072
	ds_read_b128 v[160:163], v223
	ds_read_b128 v[164:167], v223 offset:1024
	ds_read_b128 v[168:171], v223 offset:2048
	ds_read_b128 v[172:175], v223 offset:3072
	s_mov_b32 m0, s92
	ds_read_b128 v[176:179], v143
	ds_read_b128 v[180:183], v143 offset:1024
	ds_read_b128 v[184:187], v143 offset:2048
	ds_read_b128 v[188:191], v143 offset:3072
	ds_read_b128 v[192:195], v143 offset:4096
	ds_read_b128 v[196:199], v143 offset:5120
	ds_read_b128 v[200:203], v143 offset:6144
	ds_read_b128 v[204:207], v143 offset:7168
	global_load_lds_dwordx4 v128, s[44:45]
	s_mov_b32 m0, s6
	s_nop 0
	global_load_lds_dwordx4 v132, s[44:45]
	s_add_i32 m0, s57, 0xc000
	s_nop 0
	global_load_lds_dwordx4 v136, s[88:89]
	s_add_i32 m0, s57, 0xe000
	s_nop 0
	global_load_lds_dwordx4 v138, s[88:89]
	s_setprio 0
	s_waitcnt vmcnt(8)
	s_waitcnt lgkmcnt(0)
	s_barrier
	v_mfma_f32_16x16x32_bf16 v[124:127], v[144:147], v[176:179], 0
	v_mfma_f32_16x16x32_bf16 v[120:123], v[152:155], v[176:179], 0
	v_mfma_f32_16x16x32_bf16 v[116:119], v[144:147], v[184:187], 0
	v_mfma_f32_16x16x32_bf16 v[112:115], v[152:155], v[184:187], 0
	v_mfma_f32_16x16x32_bf16 v[100:103], v[144:147], v[192:195], 0
	v_mfma_f32_16x16x32_bf16 v[96:99], v[152:155], v[192:195], 0
	v_mfma_f32_16x16x32_bf16 v[84:87], v[144:147], v[200:203], 0
	v_mfma_f32_16x16x32_bf16 v[80:83], v[152:155], v[200:203], 0
	v_mfma_f32_16x16x32_bf16 v[124:127], v[148:151], v[180:183], v[124:127]
	v_mfma_f32_16x16x32_bf16 v[120:123], v[156:159], v[180:183], v[120:123]
	v_mfma_f32_16x16x32_bf16 v[116:119], v[148:151], v[188:191], v[116:119]
	v_mfma_f32_16x16x32_bf16 v[112:115], v[156:159], v[188:191], v[112:115]
	v_mfma_f32_16x16x32_bf16 v[100:103], v[148:151], v[196:199], v[100:103]
	v_mfma_f32_16x16x32_bf16 v[96:99], v[156:159], v[196:199], v[96:99]
	v_mfma_f32_16x16x32_bf16 v[84:87], v[148:151], v[204:207], v[84:87]
	v_mfma_f32_16x16x32_bf16 v[80:83], v[156:159], v[204:207], v[80:83]
	v_mfma_f32_16x16x32_bf16 v[108:111], v[160:163], v[176:179], 0
	v_mfma_f32_16x16x32_bf16 v[104:107], v[168:171], v[176:179], 0
	v_mfma_f32_16x16x32_bf16 v[92:95], v[160:163], v[184:187], 0
	v_mfma_f32_16x16x32_bf16 v[88:91], v[168:171], v[184:187], 0
	v_mfma_f32_16x16x32_bf16 v[76:79], v[160:163], v[192:195], 0
	v_mfma_f32_16x16x32_bf16 v[72:75], v[168:171], v[192:195], 0
	v_mfma_f32_16x16x32_bf16 v[68:71], v[160:163], v[200:203], 0
	v_mfma_f32_16x16x32_bf16 v[64:67], v[168:171], v[200:203], 0
	v_mfma_f32_16x16x32_bf16 v[108:111], v[164:167], v[180:183], v[108:111]
	v_mfma_f32_16x16x32_bf16 v[104:107], v[172:175], v[180:183], v[104:107]
	v_mfma_f32_16x16x32_bf16 v[92:95], v[164:167], v[188:191], v[92:95]
	v_mfma_f32_16x16x32_bf16 v[88:91], v[172:175], v[188:191], v[88:91]
	v_mfma_f32_16x16x32_bf16 v[76:79], v[164:167], v[196:199], v[76:79]
	v_mfma_f32_16x16x32_bf16 v[72:75], v[172:175], v[196:199], v[72:75]
	v_mfma_f32_16x16x32_bf16 v[68:71], v[164:167], v[204:207], v[68:71]
	v_mfma_f32_16x16x32_bf16 v[64:67], v[172:175], v[204:207], v[64:67]
	s_barrier
	s_add_i32 s44, s96, 0x10000
	s_mov_b32 m0, s44
	s_setprio 1
	ds_read_b128 v[176:179], v143 offset:16384
	ds_read_b128 v[180:183], v143 offset:17408
	ds_read_b128 v[184:187], v143 offset:18432
	ds_read_b128 v[188:191], v143 offset:19456
	ds_read_b128 v[192:195], v143 offset:20480
	ds_read_b128 v[196:199], v143 offset:21504
	ds_read_b128 v[200:203], v143 offset:22528
	ds_read_b128 v[204:207], v143 offset:23552
	global_load_lds_dwordx4 v130, s[90:91]
	s_add_i32 m0, s44, 0x2000
	s_add_u32 s44, s90, 0x80000
	s_addc_u32 s45, s91, 0
	s_add_i32 s81, s81, s96
	global_load_lds_dwordx4 v134, s[90:91]
	s_mov_b32 m0, s81
	s_nop 0
	global_load_lds_dwordx4 v130, s[44:45]
	s_add_i32 m0, s81, 0x2000
	s_nop 0
	global_load_lds_dwordx4 v134, s[44:45]
	s_setprio 0
	s_waitcnt vmcnt(6)
	s_waitcnt lgkmcnt(0)
	s_barrier
	v_mfma_f32_16x16x32_bf16 v[60:63], v[144:147], v[176:179], 0
	v_mfma_f32_16x16x32_bf16 v[56:59], v[152:155], v[176:179], 0
	v_mfma_f32_16x16x32_bf16 v[52:55], v[144:147], v[184:187], 0
	v_mfma_f32_16x16x32_bf16 v[48:51], v[152:155], v[184:187], 0
	v_mfma_f32_16x16x32_bf16 v[36:39], v[144:147], v[192:195], 0
	v_mfma_f32_16x16x32_bf16 v[32:35], v[152:155], v[192:195], 0
	v_mfma_f32_16x16x32_bf16 v[20:23], v[144:147], v[200:203], 0
	v_mfma_f32_16x16x32_bf16 v[16:19], v[152:155], v[200:203], 0
	v_mfma_f32_16x16x32_bf16 v[60:63], v[148:151], v[180:183], v[60:63]
	v_mfma_f32_16x16x32_bf16 v[56:59], v[156:159], v[180:183], v[56:59]
	v_mfma_f32_16x16x32_bf16 v[52:55], v[148:151], v[188:191], v[52:55]
	v_mfma_f32_16x16x32_bf16 v[48:51], v[156:159], v[188:191], v[48:51]
	v_mfma_f32_16x16x32_bf16 v[36:39], v[148:151], v[196:199], v[36:39]
	v_mfma_f32_16x16x32_bf16 v[32:35], v[156:159], v[196:199], v[32:35]
	v_mfma_f32_16x16x32_bf16 v[20:23], v[148:151], v[204:207], v[20:23]
	v_mfma_f32_16x16x32_bf16 v[16:19], v[156:159], v[204:207], v[16:19]
	v_mfma_f32_16x16x32_bf16 v[44:47], v[160:163], v[176:179], 0
	v_mfma_f32_16x16x32_bf16 v[40:43], v[168:171], v[176:179], 0
	v_mfma_f32_16x16x32_bf16 v[28:31], v[160:163], v[184:187], 0
	v_mfma_f32_16x16x32_bf16 v[24:27], v[168:171], v[184:187], 0
	v_mfma_f32_16x16x32_bf16 v[12:15], v[160:163], v[192:195], 0
	v_mfma_f32_16x16x32_bf16 v[8:11], v[168:171], v[192:195], 0
	v_mfma_f32_16x16x32_bf16 v[4:7], v[160:163], v[200:203], 0
	v_mfma_f32_16x16x32_bf16 v[0:3], v[168:171], v[200:203], 0
	v_mfma_f32_16x16x32_bf16 v[44:47], v[164:167], v[180:183], v[44:47]
	v_mfma_f32_16x16x32_bf16 v[40:43], v[172:175], v[180:183], v[40:43]
	v_mfma_f32_16x16x32_bf16 v[28:31], v[164:167], v[188:191], v[28:31]
	v_mfma_f32_16x16x32_bf16 v[24:27], v[172:175], v[188:191], v[24:27]
	v_mfma_f32_16x16x32_bf16 v[12:15], v[164:167], v[196:199], v[12:15]
	v_mfma_f32_16x16x32_bf16 v[8:11], v[172:175], v[196:199], v[8:11]
	v_mfma_f32_16x16x32_bf16 v[4:7], v[164:167], v[204:207], v[4:7]
	v_mfma_f32_16x16x32_bf16 v[0:3], v[172:175], v[204:207], v[0:3]
	s_barrier
	s_add_i32 s44, 0, 0x18000
	s_add_i32 s45, 0, 0x1c000
	s_setprio 1
	ds_read_b128 v[144:147], v224
	ds_read_b128 v[148:151], v224 offset:1024
	ds_read_b128 v[152:155], v224 offset:2048
	ds_read_b128 v[156:159], v224 offset:3072
	ds_read_b128 v[160:163], v225
	ds_read_b128 v[164:167], v225 offset:1024
	ds_read_b128 v[168:171], v225 offset:2048
	ds_read_b128 v[172:175], v225 offset:3072
	ds_read_b128 v[176:179], v143 offset:32768
	ds_read_b128 v[180:183], v143 offset:33792
	ds_read_b128 v[184:187], v143 offset:34816
	ds_read_b128 v[188:191], v143 offset:35840
	ds_read_b128 v[192:195], v143 offset:36864
	ds_read_b128 v[196:199], v143 offset:37888
	ds_read_b128 v[200:203], v143 offset:38912
	ds_read_b128 v[204:207], v143 offset:39936
	s_mov_b32 m0, s57
	s_nop 0
	global_load_lds_dwordx4 v128, s[22:23]
	s_mov_b32 m0, s97
	s_nop 0
	global_load_lds_dwordx4 v132, s[22:23]
	s_mov_b32 m0, s93
	s_add_u32 s22, s22, 0x80000
	s_addc_u32 s23, s23, 0
	global_load_lds_dwordx4 v128, s[22:23]
	s_mov_b32 m0, s94
	s_nop 0
	global_load_lds_dwordx4 v132, s[22:23]
	s_setprio 0
	s_waitcnt vmcnt(8)
	s_waitcnt lgkmcnt(0)
	s_barrier
	v_mfma_f32_16x16x32_bf16 v[124:127], v[144:147], v[176:179], v[124:127]
	v_mfma_f32_16x16x32_bf16 v[120:123], v[152:155], v[176:179], v[120:123]
	v_mfma_f32_16x16x32_bf16 v[116:119], v[144:147], v[184:187], v[116:119]
	v_mfma_f32_16x16x32_bf16 v[112:115], v[152:155], v[184:187], v[112:115]
	v_mfma_f32_16x16x32_bf16 v[100:103], v[144:147], v[192:195], v[100:103]
	v_mfma_f32_16x16x32_bf16 v[96:99], v[152:155], v[192:195], v[96:99]
	v_mfma_f32_16x16x32_bf16 v[84:87], v[144:147], v[200:203], v[84:87]
	v_mfma_f32_16x16x32_bf16 v[80:83], v[152:155], v[200:203], v[80:83]
	v_mfma_f32_16x16x32_bf16 v[124:127], v[148:151], v[180:183], v[124:127]
	v_mfma_f32_16x16x32_bf16 v[120:123], v[156:159], v[180:183], v[120:123]
	v_mfma_f32_16x16x32_bf16 v[116:119], v[148:151], v[188:191], v[116:119]
	v_mfma_f32_16x16x32_bf16 v[112:115], v[156:159], v[188:191], v[112:115]
	v_mfma_f32_16x16x32_bf16 v[100:103], v[148:151], v[196:199], v[100:103]
	v_mfma_f32_16x16x32_bf16 v[96:99], v[156:159], v[196:199], v[96:99]
	v_mfma_f32_16x16x32_bf16 v[84:87], v[148:151], v[204:207], v[84:87]
	v_mfma_f32_16x16x32_bf16 v[80:83], v[156:159], v[204:207], v[80:83]
	v_mfma_f32_16x16x32_bf16 v[108:111], v[160:163], v[176:179], v[108:111]
	v_mfma_f32_16x16x32_bf16 v[104:107], v[168:171], v[176:179], v[104:107]
	v_mfma_f32_16x16x32_bf16 v[92:95], v[160:163], v[184:187], v[92:95]
	v_mfma_f32_16x16x32_bf16 v[88:91], v[168:171], v[184:187], v[88:91]
	v_mfma_f32_16x16x32_bf16 v[76:79], v[160:163], v[192:195], v[76:79]
	v_mfma_f32_16x16x32_bf16 v[72:75], v[168:171], v[192:195], v[72:75]
	v_mfma_f32_16x16x32_bf16 v[68:71], v[160:163], v[200:203], v[68:71]
	v_mfma_f32_16x16x32_bf16 v[64:67], v[168:171], v[200:203], v[64:67]
	v_mfma_f32_16x16x32_bf16 v[108:111], v[164:167], v[180:183], v[108:111]
	v_mfma_f32_16x16x32_bf16 v[104:107], v[172:175], v[180:183], v[104:107]
	v_mfma_f32_16x16x32_bf16 v[92:95], v[164:167], v[188:191], v[92:95]
	v_mfma_f32_16x16x32_bf16 v[88:91], v[172:175], v[188:191], v[88:91]
	v_mfma_f32_16x16x32_bf16 v[76:79], v[164:167], v[196:199], v[76:79]
	v_mfma_f32_16x16x32_bf16 v[72:75], v[172:175], v[196:199], v[72:75]
	v_mfma_f32_16x16x32_bf16 v[68:71], v[164:167], v[204:207], v[68:71]
	v_mfma_f32_16x16x32_bf16 v[64:67], v[172:175], v[204:207], v[64:67]
	s_barrier
	s_add_i32 s22, s44, s96
	s_add_i32 m0, s22, 0xffffff80
	s_setprio 1
	ds_read_b128 v[176:179], v143 offset:49152
	ds_read_b128 v[180:183], v143 offset:50176
	ds_read_b128 v[184:187], v143 offset:51200
	ds_read_b128 v[188:191], v143 offset:52224
	ds_read_b128 v[192:195], v143 offset:53248
	ds_read_b128 v[196:199], v143 offset:54272
	ds_read_b128 v[200:203], v143 offset:55296
	ds_read_b128 v[204:207], v143 offset:56320
	global_load_lds_dwordx4 v130, s[90:91] offset:128
	s_add_i32 m0, s22, 0x1f80
	s_add_u32 s22, s90, 0x80080
	s_addc_u32 s23, s91, 0
	s_add_i32 s44, s45, s96
	global_load_lds_dwordx4 v134, s[90:91] offset:128
	s_mov_b32 m0, s44
	s_nop 0
	global_load_lds_dwordx4 v130, s[22:23]
	s_add_i32 m0, s44, 0x2000
	s_nop 0
	global_load_lds_dwordx4 v134, s[22:23]
	s_setprio 0
	s_waitcnt vmcnt(6)
	s_waitcnt lgkmcnt(0)
	s_barrier
	v_mfma_f32_16x16x32_bf16 v[60:63], v[144:147], v[176:179], v[60:63]
	v_mfma_f32_16x16x32_bf16 v[56:59], v[152:155], v[176:179], v[56:59]
	v_mfma_f32_16x16x32_bf16 v[52:55], v[144:147], v[184:187], v[52:55]
	v_mfma_f32_16x16x32_bf16 v[48:51], v[152:155], v[184:187], v[48:51]
	v_mfma_f32_16x16x32_bf16 v[36:39], v[144:147], v[192:195], v[36:39]
	v_mfma_f32_16x16x32_bf16 v[32:35], v[152:155], v[192:195], v[32:35]
	v_mfma_f32_16x16x32_bf16 v[20:23], v[144:147], v[200:203], v[20:23]
	v_mfma_f32_16x16x32_bf16 v[16:19], v[152:155], v[200:203], v[16:19]
	v_mfma_f32_16x16x32_bf16 v[60:63], v[148:151], v[180:183], v[60:63]
	v_mfma_f32_16x16x32_bf16 v[56:59], v[156:159], v[180:183], v[56:59]
	v_mfma_f32_16x16x32_bf16 v[52:55], v[148:151], v[188:191], v[52:55]
	v_mfma_f32_16x16x32_bf16 v[48:51], v[156:159], v[188:191], v[48:51]
	v_mfma_f32_16x16x32_bf16 v[36:39], v[148:151], v[196:199], v[36:39]
	v_mfma_f32_16x16x32_bf16 v[32:35], v[156:159], v[196:199], v[32:35]
	v_mfma_f32_16x16x32_bf16 v[20:23], v[148:151], v[204:207], v[20:23]
	v_mfma_f32_16x16x32_bf16 v[16:19], v[156:159], v[204:207], v[16:19]
	v_mfma_f32_16x16x32_bf16 v[44:47], v[160:163], v[176:179], v[44:47]
	v_mfma_f32_16x16x32_bf16 v[40:43], v[168:171], v[176:179], v[40:43]
	v_mfma_f32_16x16x32_bf16 v[28:31], v[160:163], v[184:187], v[28:31]
	v_mfma_f32_16x16x32_bf16 v[24:27], v[168:171], v[184:187], v[24:27]
	v_mfma_f32_16x16x32_bf16 v[12:15], v[160:163], v[192:195], v[12:15]
	v_mfma_f32_16x16x32_bf16 v[8:11], v[168:171], v[192:195], v[8:11]
	v_mfma_f32_16x16x32_bf16 v[4:7], v[160:163], v[200:203], v[4:7]
	v_mfma_f32_16x16x32_bf16 v[0:3], v[168:171], v[200:203], v[0:3]
	v_mfma_f32_16x16x32_bf16 v[44:47], v[164:167], v[180:183], v[44:47]
	v_mfma_f32_16x16x32_bf16 v[40:43], v[172:175], v[180:183], v[40:43]
	v_mfma_f32_16x16x32_bf16 v[28:31], v[164:167], v[188:191], v[28:31]
	v_mfma_f32_16x16x32_bf16 v[24:27], v[172:175], v[188:191], v[24:27]
	v_mfma_f32_16x16x32_bf16 v[12:15], v[164:167], v[196:199], v[12:15]
	v_mfma_f32_16x16x32_bf16 v[8:11], v[172:175], v[196:199], v[8:11]
	v_mfma_f32_16x16x32_bf16 v[4:7], v[164:167], v[204:207], v[4:7]
	v_mfma_f32_16x16x32_bf16 v[0:3], v[172:175], v[204:207], v[0:3]
	s_barrier
	s_add_i32 s43, s43, 2
	s_add_u32 s88, s88, 0x100
	s_addc_u32 s89, s89, 0
	s_add_u32 s41, s41, 0x100
	s_addc_u32 s42, s42, 0
	s_cmp_gt_u32 s43, 29
	s_cbranch_scc0 .LBB0_631
.LBB0_631:
	s_add_u32 s22, s88, 0xfff80080
	s_addc_u32 s23, s89, -1
	s_add_u32 s44, s88, 0xfff80000
	s_addc_u32 s45, s89, -1
	s_cmp_eq_u32 s43, 28
	s_cselect_b32 s23, s30, s23
	s_cselect_b32 s22, s31, s22
	s_cselect_b32 s91, s38, s42
	s_cselect_b32 s90, s39, s41
	s_add_i32 s81, 0, 0x14000
	s_setprio 1
	ds_read_b128 v[144:147], v222
	ds_read_b128 v[148:151], v222 offset:1024
	ds_read_b128 v[152:155], v222 offset:2048
	ds_read_b128 v[156:159], v222 offset:3072
	ds_read_b128 v[160:163], v223
	ds_read_b128 v[164:167], v223 offset:1024
	ds_read_b128 v[168:171], v223 offset:2048
	ds_read_b128 v[172:175], v223 offset:3072
	s_mov_b32 m0, s92
	ds_read_b128 v[176:179], v143
	ds_read_b128 v[180:183], v143 offset:1024
	ds_read_b128 v[184:187], v143 offset:2048
	ds_read_b128 v[188:191], v143 offset:3072
	ds_read_b128 v[192:195], v143 offset:4096
	ds_read_b128 v[196:199], v143 offset:5120
	ds_read_b128 v[200:203], v143 offset:6144
	ds_read_b128 v[204:207], v143 offset:7168
	global_load_lds_dwordx4 v128, s[44:45]
	s_mov_b32 m0, s6
	s_nop 0
	global_load_lds_dwordx4 v132, s[44:45]
	s_add_i32 m0, s57, 0xc000
	s_nop 0
	global_load_lds_dwordx4 v136, s[88:89]
	s_add_i32 m0, s57, 0xe000
	s_nop 0
	global_load_lds_dwordx4 v138, s[88:89]
	s_setprio 0
	s_waitcnt vmcnt(8)
	s_waitcnt lgkmcnt(0)
	s_barrier
	v_mfma_f32_16x16x32_bf16 v[124:127], v[144:147], v[176:179], v[124:127]
	v_mfma_f32_16x16x32_bf16 v[120:123], v[152:155], v[176:179], v[120:123]
	v_mfma_f32_16x16x32_bf16 v[116:119], v[144:147], v[184:187], v[116:119]
	v_mfma_f32_16x16x32_bf16 v[112:115], v[152:155], v[184:187], v[112:115]
	v_mfma_f32_16x16x32_bf16 v[100:103], v[144:147], v[192:195], v[100:103]
	v_mfma_f32_16x16x32_bf16 v[96:99], v[152:155], v[192:195], v[96:99]
	v_mfma_f32_16x16x32_bf16 v[84:87], v[144:147], v[200:203], v[84:87]
	v_mfma_f32_16x16x32_bf16 v[80:83], v[152:155], v[200:203], v[80:83]
	v_mfma_f32_16x16x32_bf16 v[124:127], v[148:151], v[180:183], v[124:127]
	v_mfma_f32_16x16x32_bf16 v[120:123], v[156:159], v[180:183], v[120:123]
	v_mfma_f32_16x16x32_bf16 v[116:119], v[148:151], v[188:191], v[116:119]
	v_mfma_f32_16x16x32_bf16 v[112:115], v[156:159], v[188:191], v[112:115]
	v_mfma_f32_16x16x32_bf16 v[100:103], v[148:151], v[196:199], v[100:103]
	v_mfma_f32_16x16x32_bf16 v[96:99], v[156:159], v[196:199], v[96:99]
	v_mfma_f32_16x16x32_bf16 v[84:87], v[148:151], v[204:207], v[84:87]
	v_mfma_f32_16x16x32_bf16 v[80:83], v[156:159], v[204:207], v[80:83]
	v_mfma_f32_16x16x32_bf16 v[108:111], v[160:163], v[176:179], v[108:111]
	v_mfma_f32_16x16x32_bf16 v[104:107], v[168:171], v[176:179], v[104:107]
	v_mfma_f32_16x16x32_bf16 v[92:95], v[160:163], v[184:187], v[92:95]
	v_mfma_f32_16x16x32_bf16 v[88:91], v[168:171], v[184:187], v[88:91]
	v_mfma_f32_16x16x32_bf16 v[76:79], v[160:163], v[192:195], v[76:79]
	v_mfma_f32_16x16x32_bf16 v[72:75], v[168:171], v[192:195], v[72:75]
	v_mfma_f32_16x16x32_bf16 v[68:71], v[160:163], v[200:203], v[68:71]
	v_mfma_f32_16x16x32_bf16 v[64:67], v[168:171], v[200:203], v[64:67]
	v_mfma_f32_16x16x32_bf16 v[108:111], v[164:167], v[180:183], v[108:111]
	v_mfma_f32_16x16x32_bf16 v[104:107], v[172:175], v[180:183], v[104:107]
	v_mfma_f32_16x16x32_bf16 v[92:95], v[164:167], v[188:191], v[92:95]
	v_mfma_f32_16x16x32_bf16 v[88:91], v[172:175], v[188:191], v[88:91]
	v_mfma_f32_16x16x32_bf16 v[76:79], v[164:167], v[196:199], v[76:79]
	v_mfma_f32_16x16x32_bf16 v[72:75], v[172:175], v[196:199], v[72:75]
	v_mfma_f32_16x16x32_bf16 v[68:71], v[164:167], v[204:207], v[68:71]
	v_mfma_f32_16x16x32_bf16 v[64:67], v[172:175], v[204:207], v[64:67]
	s_barrier
	s_add_i32 s44, s96, 0x10000
	s_mov_b32 m0, s44
	s_setprio 1
	ds_read_b128 v[176:179], v143 offset:16384
	ds_read_b128 v[180:183], v143 offset:17408
	ds_read_b128 v[184:187], v143 offset:18432
	ds_read_b128 v[188:191], v143 offset:19456
	ds_read_b128 v[192:195], v143 offset:20480
	ds_read_b128 v[196:199], v143 offset:21504
	ds_read_b128 v[200:203], v143 offset:22528
	ds_read_b128 v[204:207], v143 offset:23552
	global_load_lds_dwordx4 v130, s[90:91]
	s_add_i32 m0, s44, 0x2000
	s_add_u32 s44, s90, 0x80000
	s_addc_u32 s45, s91, 0
	s_add_i32 s81, s81, s96
	global_load_lds_dwordx4 v134, s[90:91]
	s_mov_b32 m0, s81
	s_nop 0
	global_load_lds_dwordx4 v130, s[44:45]
	s_add_i32 m0, s81, 0x2000
	s_nop 0
	global_load_lds_dwordx4 v134, s[44:45]
	s_setprio 0
	s_waitcnt vmcnt(6)
	s_waitcnt lgkmcnt(0)
	s_barrier
	v_mfma_f32_16x16x32_bf16 v[60:63], v[144:147], v[176:179], v[60:63]
	v_mfma_f32_16x16x32_bf16 v[56:59], v[152:155], v[176:179], v[56:59]
	v_mfma_f32_16x16x32_bf16 v[52:55], v[144:147], v[184:187], v[52:55]
	v_mfma_f32_16x16x32_bf16 v[48:51], v[152:155], v[184:187], v[48:51]
	v_mfma_f32_16x16x32_bf16 v[36:39], v[144:147], v[192:195], v[36:39]
	v_mfma_f32_16x16x32_bf16 v[32:35], v[152:155], v[192:195], v[32:35]
	v_mfma_f32_16x16x32_bf16 v[20:23], v[144:147], v[200:203], v[20:23]
	v_mfma_f32_16x16x32_bf16 v[16:19], v[152:155], v[200:203], v[16:19]
	v_mfma_f32_16x16x32_bf16 v[60:63], v[148:151], v[180:183], v[60:63]
	v_mfma_f32_16x16x32_bf16 v[56:59], v[156:159], v[180:183], v[56:59]
	v_mfma_f32_16x16x32_bf16 v[52:55], v[148:151], v[188:191], v[52:55]
	v_mfma_f32_16x16x32_bf16 v[48:51], v[156:159], v[188:191], v[48:51]
	v_mfma_f32_16x16x32_bf16 v[36:39], v[148:151], v[196:199], v[36:39]
	v_mfma_f32_16x16x32_bf16 v[32:35], v[156:159], v[196:199], v[32:35]
	v_mfma_f32_16x16x32_bf16 v[20:23], v[148:151], v[204:207], v[20:23]
	v_mfma_f32_16x16x32_bf16 v[16:19], v[156:159], v[204:207], v[16:19]
	v_mfma_f32_16x16x32_bf16 v[44:47], v[160:163], v[176:179], v[44:47]
	v_mfma_f32_16x16x32_bf16 v[40:43], v[168:171], v[176:179], v[40:43]
	v_mfma_f32_16x16x32_bf16 v[28:31], v[160:163], v[184:187], v[28:31]
	v_mfma_f32_16x16x32_bf16 v[24:27], v[168:171], v[184:187], v[24:27]
	v_mfma_f32_16x16x32_bf16 v[12:15], v[160:163], v[192:195], v[12:15]
	v_mfma_f32_16x16x32_bf16 v[8:11], v[168:171], v[192:195], v[8:11]
	v_mfma_f32_16x16x32_bf16 v[4:7], v[160:163], v[200:203], v[4:7]
	v_mfma_f32_16x16x32_bf16 v[0:3], v[168:171], v[200:203], v[0:3]
	v_mfma_f32_16x16x32_bf16 v[44:47], v[164:167], v[180:183], v[44:47]
	v_mfma_f32_16x16x32_bf16 v[40:43], v[172:175], v[180:183], v[40:43]
	v_mfma_f32_16x16x32_bf16 v[28:31], v[164:167], v[188:191], v[28:31]
	v_mfma_f32_16x16x32_bf16 v[24:27], v[172:175], v[188:191], v[24:27]
	v_mfma_f32_16x16x32_bf16 v[12:15], v[164:167], v[196:199], v[12:15]
	v_mfma_f32_16x16x32_bf16 v[8:11], v[172:175], v[196:199], v[8:11]
	v_mfma_f32_16x16x32_bf16 v[4:7], v[164:167], v[204:207], v[4:7]
	v_mfma_f32_16x16x32_bf16 v[0:3], v[172:175], v[204:207], v[0:3]
	s_barrier
	s_add_i32 s44, 0, 0x18000
	s_add_i32 s45, 0, 0x1c000
	s_setprio 1
	ds_read_b128 v[144:147], v224
	ds_read_b128 v[148:151], v224 offset:1024
	ds_read_b128 v[152:155], v224 offset:2048
	ds_read_b128 v[156:159], v224 offset:3072
	ds_read_b128 v[160:163], v225
	ds_read_b128 v[164:167], v225 offset:1024
	ds_read_b128 v[168:171], v225 offset:2048
	ds_read_b128 v[172:175], v225 offset:3072
	ds_read_b128 v[176:179], v143 offset:32768
	ds_read_b128 v[180:183], v143 offset:33792
	ds_read_b128 v[184:187], v143 offset:34816
	ds_read_b128 v[188:191], v143 offset:35840
	ds_read_b128 v[192:195], v143 offset:36864
	ds_read_b128 v[196:199], v143 offset:37888
	ds_read_b128 v[200:203], v143 offset:38912
	ds_read_b128 v[204:207], v143 offset:39936
	s_mov_b32 m0, s57
	s_nop 0
	global_load_lds_dwordx4 v128, s[22:23]
	s_mov_b32 m0, s97
	s_nop 0
	global_load_lds_dwordx4 v132, s[22:23]
	s_mov_b32 m0, s93
	s_add_u32 s22, s22, 0x80000
	s_addc_u32 s23, s23, 0
	global_load_lds_dwordx4 v128, s[22:23]
	s_mov_b32 m0, s94
	s_nop 0
	global_load_lds_dwordx4 v132, s[22:23]
	s_setprio 0
	s_waitcnt vmcnt(8)
	s_waitcnt lgkmcnt(0)
	s_barrier
	v_mfma_f32_16x16x32_bf16 v[124:127], v[144:147], v[176:179], v[124:127]
	v_mfma_f32_16x16x32_bf16 v[120:123], v[152:155], v[176:179], v[120:123]
	v_mfma_f32_16x16x32_bf16 v[116:119], v[144:147], v[184:187], v[116:119]
	v_mfma_f32_16x16x32_bf16 v[112:115], v[152:155], v[184:187], v[112:115]
	v_mfma_f32_16x16x32_bf16 v[100:103], v[144:147], v[192:195], v[100:103]
	v_mfma_f32_16x16x32_bf16 v[96:99], v[152:155], v[192:195], v[96:99]
	v_mfma_f32_16x16x32_bf16 v[84:87], v[144:147], v[200:203], v[84:87]
	v_mfma_f32_16x16x32_bf16 v[80:83], v[152:155], v[200:203], v[80:83]
	v_mfma_f32_16x16x32_bf16 v[124:127], v[148:151], v[180:183], v[124:127]
	v_mfma_f32_16x16x32_bf16 v[120:123], v[156:159], v[180:183], v[120:123]
	v_mfma_f32_16x16x32_bf16 v[116:119], v[148:151], v[188:191], v[116:119]
	v_mfma_f32_16x16x32_bf16 v[112:115], v[156:159], v[188:191], v[112:115]
	v_mfma_f32_16x16x32_bf16 v[100:103], v[148:151], v[196:199], v[100:103]
	v_mfma_f32_16x16x32_bf16 v[96:99], v[156:159], v[196:199], v[96:99]
	v_mfma_f32_16x16x32_bf16 v[84:87], v[148:151], v[204:207], v[84:87]
	v_mfma_f32_16x16x32_bf16 v[80:83], v[156:159], v[204:207], v[80:83]
	v_mfma_f32_16x16x32_bf16 v[108:111], v[160:163], v[176:179], v[108:111]
	v_mfma_f32_16x16x32_bf16 v[104:107], v[168:171], v[176:179], v[104:107]
	v_mfma_f32_16x16x32_bf16 v[92:95], v[160:163], v[184:187], v[92:95]
	v_mfma_f32_16x16x32_bf16 v[88:91], v[168:171], v[184:187], v[88:91]
	v_mfma_f32_16x16x32_bf16 v[76:79], v[160:163], v[192:195], v[76:79]
	v_mfma_f32_16x16x32_bf16 v[72:75], v[168:171], v[192:195], v[72:75]
	v_mfma_f32_16x16x32_bf16 v[68:71], v[160:163], v[200:203], v[68:71]
	v_mfma_f32_16x16x32_bf16 v[64:67], v[168:171], v[200:203], v[64:67]
	v_mfma_f32_16x16x32_bf16 v[108:111], v[164:167], v[180:183], v[108:111]
	v_mfma_f32_16x16x32_bf16 v[104:107], v[172:175], v[180:183], v[104:107]
	v_mfma_f32_16x16x32_bf16 v[92:95], v[164:167], v[188:191], v[92:95]
	v_mfma_f32_16x16x32_bf16 v[88:91], v[172:175], v[188:191], v[88:91]
	v_mfma_f32_16x16x32_bf16 v[76:79], v[164:167], v[196:199], v[76:79]
	v_mfma_f32_16x16x32_bf16 v[72:75], v[172:175], v[196:199], v[72:75]
	v_mfma_f32_16x16x32_bf16 v[68:71], v[164:167], v[204:207], v[68:71]
	v_mfma_f32_16x16x32_bf16 v[64:67], v[172:175], v[204:207], v[64:67]
	s_barrier
	s_add_i32 s22, s44, s96
	s_add_i32 m0, s22, 0xffffff80
	s_setprio 1
	ds_read_b128 v[176:179], v143 offset:49152
	ds_read_b128 v[180:183], v143 offset:50176
	ds_read_b128 v[184:187], v143 offset:51200
	ds_read_b128 v[188:191], v143 offset:52224
	ds_read_b128 v[192:195], v143 offset:53248
	ds_read_b128 v[196:199], v143 offset:54272
	ds_read_b128 v[200:203], v143 offset:55296
	ds_read_b128 v[204:207], v143 offset:56320
	global_load_lds_dwordx4 v130, s[90:91] offset:128
	s_add_i32 m0, s22, 0x1f80
	s_add_u32 s22, s90, 0x80080
	s_addc_u32 s23, s91, 0
	s_add_i32 s44, s45, s96
	global_load_lds_dwordx4 v134, s[90:91] offset:128
	s_mov_b32 m0, s44
	s_nop 0
	global_load_lds_dwordx4 v130, s[22:23]
	s_add_i32 m0, s44, 0x2000
	s_nop 0
	global_load_lds_dwordx4 v134, s[22:23]
	s_setprio 0
	s_waitcnt vmcnt(6)
	s_waitcnt lgkmcnt(0)
	s_barrier
	v_mfma_f32_16x16x32_bf16 v[60:63], v[144:147], v[176:179], v[60:63]
	v_mfma_f32_16x16x32_bf16 v[56:59], v[152:155], v[176:179], v[56:59]
	v_mfma_f32_16x16x32_bf16 v[52:55], v[144:147], v[184:187], v[52:55]
	v_mfma_f32_16x16x32_bf16 v[48:51], v[152:155], v[184:187], v[48:51]
	v_mfma_f32_16x16x32_bf16 v[36:39], v[144:147], v[192:195], v[36:39]
	v_mfma_f32_16x16x32_bf16 v[32:35], v[152:155], v[192:195], v[32:35]
	v_mfma_f32_16x16x32_bf16 v[20:23], v[144:147], v[200:203], v[20:23]
	v_mfma_f32_16x16x32_bf16 v[16:19], v[152:155], v[200:203], v[16:19]
	v_mfma_f32_16x16x32_bf16 v[60:63], v[148:151], v[180:183], v[60:63]
	v_mfma_f32_16x16x32_bf16 v[56:59], v[156:159], v[180:183], v[56:59]
	v_mfma_f32_16x16x32_bf16 v[52:55], v[148:151], v[188:191], v[52:55]
	v_mfma_f32_16x16x32_bf16 v[48:51], v[156:159], v[188:191], v[48:51]
	v_mfma_f32_16x16x32_bf16 v[36:39], v[148:151], v[196:199], v[36:39]
	v_mfma_f32_16x16x32_bf16 v[32:35], v[156:159], v[196:199], v[32:35]
	v_mfma_f32_16x16x32_bf16 v[20:23], v[148:151], v[204:207], v[20:23]
	v_mfma_f32_16x16x32_bf16 v[16:19], v[156:159], v[204:207], v[16:19]
	v_mfma_f32_16x16x32_bf16 v[44:47], v[160:163], v[176:179], v[44:47]
	v_mfma_f32_16x16x32_bf16 v[40:43], v[168:171], v[176:179], v[40:43]
	v_mfma_f32_16x16x32_bf16 v[28:31], v[160:163], v[184:187], v[28:31]
	v_mfma_f32_16x16x32_bf16 v[24:27], v[168:171], v[184:187], v[24:27]
	v_mfma_f32_16x16x32_bf16 v[12:15], v[160:163], v[192:195], v[12:15]
	v_mfma_f32_16x16x32_bf16 v[8:11], v[168:171], v[192:195], v[8:11]
	v_mfma_f32_16x16x32_bf16 v[4:7], v[160:163], v[200:203], v[4:7]
	v_mfma_f32_16x16x32_bf16 v[0:3], v[168:171], v[200:203], v[0:3]
	v_mfma_f32_16x16x32_bf16 v[44:47], v[164:167], v[180:183], v[44:47]
	v_mfma_f32_16x16x32_bf16 v[40:43], v[172:175], v[180:183], v[40:43]
	v_mfma_f32_16x16x32_bf16 v[28:31], v[164:167], v[188:191], v[28:31]
	v_mfma_f32_16x16x32_bf16 v[24:27], v[172:175], v[188:191], v[24:27]
	v_mfma_f32_16x16x32_bf16 v[12:15], v[164:167], v[196:199], v[12:15]
	v_mfma_f32_16x16x32_bf16 v[8:11], v[172:175], v[196:199], v[8:11]
	v_mfma_f32_16x16x32_bf16 v[4:7], v[164:167], v[204:207], v[4:7]
	v_mfma_f32_16x16x32_bf16 v[0:3], v[172:175], v[204:207], v[0:3]
	s_barrier
	s_add_i32 s43, s43, 2
	s_add_u32 s88, s88, 0x100
	s_addc_u32 s89, s89, 0
	s_add_u32 s41, s41, 0x100
	s_addc_u32 s42, s42, 0
	s_cmp_gt_u32 s43, 29
	s_cbranch_scc0 .LBB0_631
	s_cmp_eq_u32 s40, 0
	s_cselect_b64 s[30:31], -1, 0
	s_cmp_lg_u32 s40, 0
	s_mov_b64 s[38:39], -1
	s_cbranch_scc0 .LBB0_634
	s_lshl_b32 s22, s80, 8
	s_or_b32 s22, s22, s53
	s_ashr_i32 s22, s22, 6
	s_mov_b64 s[38:39], 0

.LBB0_1259:
	s_add_u32 s22, s92, s76
	s_addc_u32 s23, s93, s77
	s_add_u32 s80, s96, s76
	s_addc_u32 s81, s97, s77
	s_cmp_eq_u32 s44, 0
	s_cselect_b32 s23, s15, s23
	s_cselect_b32 s22, s91, s22
	s_cselect_b32 vcc_hi, s89, s81
	s_cselect_b32 vcc_lo, s8, s80
	s_add_u32 s80, s92, s76
	s_addc_u32 s81, s93, s77
	s_sub_u32 s80, s80, 0x80
	s_subb_u32 s81, s81, 0
	s_add_i32 s83, 0, 0x14000
	s_setprio 1
	ds_read_b128 v[142:145], v222
	ds_read_b128 v[146:149], v222 offset:1024
	ds_read_b128 v[150:153], v222 offset:2048
	ds_read_b128 v[154:157], v222 offset:3072
	ds_read_b128 v[158:161], v223
	ds_read_b128 v[162:165], v223 offset:1024
	ds_read_b128 v[166:169], v223 offset:2048
	ds_read_b128 v[170:173], v223 offset:3072
	s_mov_b32 m0, s9
	ds_read_b128 v[174:177], v140
	ds_read_b128 v[178:181], v140 offset:1024
	ds_read_b128 v[182:185], v140 offset:2048
	ds_read_b128 v[186:189], v140 offset:3072
	ds_read_b128 v[190:193], v140 offset:4096
	ds_read_b128 v[194:197], v140 offset:5120
	ds_read_b128 v[198:201], v140 offset:6144
	ds_read_b128 v[202:205], v140 offset:7168
	global_load_lds_dwordx4 v208, s[80:81]
	s_mov_b32 m0, s12
	s_nop 0
	global_load_lds_dwordx4 v128, s[80:81]
	s_add_i32 m0, s45, 0xc000
	s_nop 0
	global_load_lds_dwordx4 v136, s[92:93]
	s_add_i32 m0, s45, 0xe000
	s_nop 0
	global_load_lds_dwordx4 v134, s[92:93]
	s_setprio 0
	s_waitcnt vmcnt(8)
	s_waitcnt lgkmcnt(0)
	s_barrier
	v_mfma_f32_16x16x32_bf16 v[124:127], v[142:145], v[174:177], v[124:127]
	v_mfma_f32_16x16x32_bf16 v[120:123], v[150:153], v[174:177], v[120:123]
	v_mfma_f32_16x16x32_bf16 v[108:111], v[142:145], v[182:185], v[108:111]
	v_mfma_f32_16x16x32_bf16 v[104:107], v[150:153], v[182:185], v[104:107]
	v_mfma_f32_16x16x32_bf16 v[92:95], v[142:145], v[190:193], v[92:95]
	v_mfma_f32_16x16x32_bf16 v[88:91], v[150:153], v[190:193], v[88:91]
	v_mfma_f32_16x16x32_bf16 v[76:79], v[142:145], v[198:201], v[76:79]
	v_mfma_f32_16x16x32_bf16 v[72:75], v[150:153], v[198:201], v[72:75]
	v_mfma_f32_16x16x32_bf16 v[124:127], v[146:149], v[178:181], v[124:127]
	v_mfma_f32_16x16x32_bf16 v[120:123], v[154:157], v[178:181], v[120:123]
	v_mfma_f32_16x16x32_bf16 v[108:111], v[146:149], v[186:189], v[108:111]
	v_mfma_f32_16x16x32_bf16 v[104:107], v[154:157], v[186:189], v[104:107]
	v_mfma_f32_16x16x32_bf16 v[92:95], v[146:149], v[194:197], v[92:95]
	v_mfma_f32_16x16x32_bf16 v[88:91], v[154:157], v[194:197], v[88:91]
	v_mfma_f32_16x16x32_bf16 v[76:79], v[146:149], v[202:205], v[76:79]
	v_mfma_f32_16x16x32_bf16 v[72:75], v[154:157], v[202:205], v[72:75]
	v_mfma_f32_16x16x32_bf16 v[116:119], v[158:161], v[174:177], v[116:119]
	v_mfma_f32_16x16x32_bf16 v[112:115], v[166:169], v[174:177], v[112:115]
	v_mfma_f32_16x16x32_bf16 v[100:103], v[158:161], v[182:185], v[100:103]
	v_mfma_f32_16x16x32_bf16 v[96:99], v[166:169], v[182:185], v[96:99]
	v_mfma_f32_16x16x32_bf16 v[84:87], v[158:161], v[190:193], v[84:87]
	v_mfma_f32_16x16x32_bf16 v[80:83], v[166:169], v[190:193], v[80:83]
	v_mfma_f32_16x16x32_bf16 v[68:71], v[158:161], v[198:201], v[68:71]
	v_mfma_f32_16x16x32_bf16 v[64:67], v[166:169], v[198:201], v[64:67]
	v_mfma_f32_16x16x32_bf16 v[116:119], v[162:165], v[178:181], v[116:119]
	v_mfma_f32_16x16x32_bf16 v[112:115], v[170:173], v[178:181], v[112:115]
	v_mfma_f32_16x16x32_bf16 v[100:103], v[162:165], v[186:189], v[100:103]
	v_mfma_f32_16x16x32_bf16 v[96:99], v[170:173], v[186:189], v[96:99]
	v_mfma_f32_16x16x32_bf16 v[84:87], v[162:165], v[194:197], v[84:87]
	v_mfma_f32_16x16x32_bf16 v[80:83], v[170:173], v[194:197], v[80:83]
	v_mfma_f32_16x16x32_bf16 v[68:71], v[162:165], v[202:205], v[68:71]
	v_mfma_f32_16x16x32_bf16 v[64:67], v[170:173], v[202:205], v[64:67]
	s_barrier
	s_add_i32 s80, s43, 0x10000
	s_mov_b32 m0, s80
	s_setprio 1
	ds_read_b128 v[174:177], v140 offset:16384
	ds_read_b128 v[178:181], v140 offset:17408
	ds_read_b128 v[182:185], v140 offset:18432
	ds_read_b128 v[186:189], v140 offset:19456
	ds_read_b128 v[190:193], v140 offset:20480
	ds_read_b128 v[194:197], v140 offset:21504
	ds_read_b128 v[198:201], v140 offset:22528
	ds_read_b128 v[202:205], v140 offset:23552
	global_load_lds_dwordx4 v208, vcc
	s_add_i32 m0, s80, 0x2000
	s_add_u32 s80, vcc_lo, 0x80000
	s_addc_u32 s81, vcc_hi, 0
	s_add_i32 s83, s83, s43
	global_load_lds_dwordx4 v128, vcc
	s_mov_b32 m0, s83
	s_nop 0
	global_load_lds_dwordx4 v208, s[80:81]
	s_add_i32 m0, s83, 0x2000
	s_nop 0
	global_load_lds_dwordx4 v128, s[80:81]
	s_setprio 0
	s_waitcnt vmcnt(6)
	s_waitcnt lgkmcnt(0)
	s_barrier
	v_mfma_f32_16x16x32_bf16 v[60:63], v[142:145], v[174:177], v[60:63]
	v_mfma_f32_16x16x32_bf16 v[56:59], v[150:153], v[174:177], v[56:59]
	v_mfma_f32_16x16x32_bf16 v[44:47], v[142:145], v[182:185], v[44:47]
	v_mfma_f32_16x16x32_bf16 v[40:43], v[150:153], v[182:185], v[40:43]
	v_mfma_f32_16x16x32_bf16 v[28:31], v[142:145], v[190:193], v[28:31]
	v_mfma_f32_16x16x32_bf16 v[24:27], v[150:153], v[190:193], v[24:27]
	v_mfma_f32_16x16x32_bf16 v[12:15], v[142:145], v[198:201], v[12:15]
	v_mfma_f32_16x16x32_bf16 v[8:11], v[150:153], v[198:201], v[8:11]
	v_mfma_f32_16x16x32_bf16 v[60:63], v[146:149], v[178:181], v[60:63]
	v_mfma_f32_16x16x32_bf16 v[56:59], v[154:157], v[178:181], v[56:59]
	v_mfma_f32_16x16x32_bf16 v[44:47], v[146:149], v[186:189], v[44:47]
	v_mfma_f32_16x16x32_bf16 v[40:43], v[154:157], v[186:189], v[40:43]
	v_mfma_f32_16x16x32_bf16 v[28:31], v[146:149], v[194:197], v[28:31]
	v_mfma_f32_16x16x32_bf16 v[24:27], v[154:157], v[194:197], v[24:27]
	v_mfma_f32_16x16x32_bf16 v[12:15], v[146:149], v[202:205], v[12:15]
	v_mfma_f32_16x16x32_bf16 v[8:11], v[154:157], v[202:205], v[8:11]
	v_mfma_f32_16x16x32_bf16 v[52:55], v[158:161], v[174:177], v[52:55]
	v_mfma_f32_16x16x32_bf16 v[48:51], v[166:169], v[174:177], v[48:51]
	v_mfma_f32_16x16x32_bf16 v[36:39], v[158:161], v[182:185], v[36:39]
	v_mfma_f32_16x16x32_bf16 v[32:35], v[166:169], v[182:185], v[32:35]
	v_mfma_f32_16x16x32_bf16 v[20:23], v[158:161], v[190:193], v[20:23]
	v_mfma_f32_16x16x32_bf16 v[16:19], v[166:169], v[190:193], v[16:19]
	v_mfma_f32_16x16x32_bf16 v[4:7], v[158:161], v[198:201], v[4:7]
	v_mfma_f32_16x16x32_bf16 v[0:3], v[166:169], v[198:201], v[0:3]
	v_mfma_f32_16x16x32_bf16 v[52:55], v[162:165], v[178:181], v[52:55]
	v_mfma_f32_16x16x32_bf16 v[48:51], v[170:173], v[178:181], v[48:51]
	v_mfma_f32_16x16x32_bf16 v[36:39], v[162:165], v[186:189], v[36:39]
	v_mfma_f32_16x16x32_bf16 v[32:35], v[170:173], v[186:189], v[32:35]
	v_mfma_f32_16x16x32_bf16 v[20:23], v[162:165], v[194:197], v[20:23]
	v_mfma_f32_16x16x32_bf16 v[16:19], v[170:173], v[194:197], v[16:19]
	v_mfma_f32_16x16x32_bf16 v[4:7], v[162:165], v[202:205], v[4:7]
	v_mfma_f32_16x16x32_bf16 v[0:3], v[170:173], v[202:205], v[0:3]
	s_barrier
	s_add_i32 s80, 0, 0x18000
	s_add_i32 s81, 0, 0x1c000
	s_setprio 1
	ds_read_b128 v[142:145], v224
	ds_read_b128 v[146:149], v224 offset:1024
	ds_read_b128 v[150:153], v224 offset:2048
	ds_read_b128 v[154:157], v224 offset:3072
	ds_read_b128 v[158:161], v225
	ds_read_b128 v[162:165], v225 offset:1024
	ds_read_b128 v[166:169], v225 offset:2048
	ds_read_b128 v[170:173], v225 offset:3072
	ds_read_b128 v[174:177], v140 offset:32768
	ds_read_b128 v[178:181], v140 offset:33792
	ds_read_b128 v[182:185], v140 offset:34816
	ds_read_b128 v[186:189], v140 offset:35840
	ds_read_b128 v[190:193], v140 offset:36864
	ds_read_b128 v[194:197], v140 offset:37888
	ds_read_b128 v[198:201], v140 offset:38912
	ds_read_b128 v[202:205], v140 offset:39936
	s_mov_b32 m0, s45
	s_nop 0
	global_load_lds_dwordx4 v208, s[22:23]
	s_mov_b32 m0, s52
	s_nop 0
	global_load_lds_dwordx4 v128, s[22:23]
	s_mov_b32 m0, s53
	s_add_u32 s22, s22, 0x80000
	s_addc_u32 s23, s23, 0
	global_load_lds_dwordx4 v208, s[22:23]
	s_mov_b32 m0, s85
	s_nop 0
	global_load_lds_dwordx4 v128, s[22:23]
	s_setprio 0
	s_waitcnt vmcnt(8)
	s_waitcnt lgkmcnt(0)
	s_barrier
	v_mfma_f32_16x16x32_bf16 v[124:127], v[142:145], v[174:177], v[124:127]
	v_mfma_f32_16x16x32_bf16 v[120:123], v[150:153], v[174:177], v[120:123]
	v_mfma_f32_16x16x32_bf16 v[108:111], v[142:145], v[182:185], v[108:111]
	v_mfma_f32_16x16x32_bf16 v[104:107], v[150:153], v[182:185], v[104:107]
	v_mfma_f32_16x16x32_bf16 v[92:95], v[142:145], v[190:193], v[92:95]
	v_mfma_f32_16x16x32_bf16 v[88:91], v[150:153], v[190:193], v[88:91]
	v_mfma_f32_16x16x32_bf16 v[76:79], v[142:145], v[198:201], v[76:79]
	v_mfma_f32_16x16x32_bf16 v[72:75], v[150:153], v[198:201], v[72:75]
	v_mfma_f32_16x16x32_bf16 v[124:127], v[146:149], v[178:181], v[124:127]
	v_mfma_f32_16x16x32_bf16 v[120:123], v[154:157], v[178:181], v[120:123]
	v_mfma_f32_16x16x32_bf16 v[108:111], v[146:149], v[186:189], v[108:111]
	v_mfma_f32_16x16x32_bf16 v[104:107], v[154:157], v[186:189], v[104:107]
	v_mfma_f32_16x16x32_bf16 v[92:95], v[146:149], v[194:197], v[92:95]
	v_mfma_f32_16x16x32_bf16 v[88:91], v[154:157], v[194:197], v[88:91]
	v_mfma_f32_16x16x32_bf16 v[76:79], v[146:149], v[202:205], v[76:79]
	v_mfma_f32_16x16x32_bf16 v[72:75], v[154:157], v[202:205], v[72:75]
	v_mfma_f32_16x16x32_bf16 v[116:119], v[158:161], v[174:177], v[116:119]
	v_mfma_f32_16x16x32_bf16 v[112:115], v[166:169], v[174:177], v[112:115]
	v_mfma_f32_16x16x32_bf16 v[100:103], v[158:161], v[182:185], v[100:103]
	v_mfma_f32_16x16x32_bf16 v[96:99], v[166:169], v[182:185], v[96:99]
	v_mfma_f32_16x16x32_bf16 v[84:87], v[158:161], v[190:193], v[84:87]
	v_mfma_f32_16x16x32_bf16 v[80:83], v[166:169], v[190:193], v[80:83]
	v_mfma_f32_16x16x32_bf16 v[68:71], v[158:161], v[198:201], v[68:71]
	v_mfma_f32_16x16x32_bf16 v[64:67], v[166:169], v[198:201], v[64:67]
	v_mfma_f32_16x16x32_bf16 v[116:119], v[162:165], v[178:181], v[116:119]
	v_mfma_f32_16x16x32_bf16 v[112:115], v[170:173], v[178:181], v[112:115]
	v_mfma_f32_16x16x32_bf16 v[100:103], v[162:165], v[186:189], v[100:103]
	v_mfma_f32_16x16x32_bf16 v[96:99], v[170:173], v[186:189], v[96:99]
	v_mfma_f32_16x16x32_bf16 v[84:87], v[162:165], v[194:197], v[84:87]
	v_mfma_f32_16x16x32_bf16 v[80:83], v[170:173], v[194:197], v[80:83]
	v_mfma_f32_16x16x32_bf16 v[68:71], v[162:165], v[202:205], v[68:71]
	v_mfma_f32_16x16x32_bf16 v[64:67], v[170:173], v[202:205], v[64:67]
	s_barrier
	s_add_i32 s22, s80, s43
	s_add_i32 m0, s22, 0xffffff80
	s_setprio 1
	ds_read_b128 v[174:177], v140 offset:49152
	ds_read_b128 v[178:181], v140 offset:50176
	ds_read_b128 v[182:185], v140 offset:51200
	ds_read_b128 v[186:189], v140 offset:52224
	ds_read_b128 v[190:193], v140 offset:53248
	ds_read_b128 v[194:197], v140 offset:54272
	ds_read_b128 v[198:201], v140 offset:55296
	ds_read_b128 v[202:205], v140 offset:56320
	global_load_lds_dwordx4 v208, vcc offset:128
	s_add_i32 m0, s22, 0x1f80
	s_add_u32 s22, vcc_lo, 0x80080
	s_addc_u32 s23, vcc_hi, 0
	s_add_i32 s80, s81, s43
	global_load_lds_dwordx4 v128, vcc offset:128
	s_mov_b32 m0, s80
	s_nop 0
	global_load_lds_dwordx4 v208, s[22:23]
	s_add_i32 m0, s80, 0x2000
	s_nop 0
	global_load_lds_dwordx4 v128, s[22:23]
	s_setprio 0
	s_waitcnt vmcnt(6)
	s_waitcnt lgkmcnt(0)
	s_barrier
	v_mfma_f32_16x16x32_bf16 v[60:63], v[142:145], v[174:177], v[60:63]
	v_mfma_f32_16x16x32_bf16 v[56:59], v[150:153], v[174:177], v[56:59]
	v_mfma_f32_16x16x32_bf16 v[44:47], v[142:145], v[182:185], v[44:47]
	v_mfma_f32_16x16x32_bf16 v[40:43], v[150:153], v[182:185], v[40:43]
	v_mfma_f32_16x16x32_bf16 v[28:31], v[142:145], v[190:193], v[28:31]
	v_mfma_f32_16x16x32_bf16 v[24:27], v[150:153], v[190:193], v[24:27]
	v_mfma_f32_16x16x32_bf16 v[12:15], v[142:145], v[198:201], v[12:15]
	v_mfma_f32_16x16x32_bf16 v[8:11], v[150:153], v[198:201], v[8:11]
	v_mfma_f32_16x16x32_bf16 v[60:63], v[146:149], v[178:181], v[60:63]
	v_mfma_f32_16x16x32_bf16 v[56:59], v[154:157], v[178:181], v[56:59]
	v_mfma_f32_16x16x32_bf16 v[44:47], v[146:149], v[186:189], v[44:47]
	v_mfma_f32_16x16x32_bf16 v[40:43], v[154:157], v[186:189], v[40:43]
	v_mfma_f32_16x16x32_bf16 v[28:31], v[146:149], v[194:197], v[28:31]
	v_mfma_f32_16x16x32_bf16 v[24:27], v[154:157], v[194:197], v[24:27]
	v_mfma_f32_16x16x32_bf16 v[12:15], v[146:149], v[202:205], v[12:15]
	v_mfma_f32_16x16x32_bf16 v[8:11], v[154:157], v[202:205], v[8:11]
	v_mfma_f32_16x16x32_bf16 v[52:55], v[158:161], v[174:177], v[52:55]
	v_mfma_f32_16x16x32_bf16 v[48:51], v[166:169], v[174:177], v[48:51]
	v_mfma_f32_16x16x32_bf16 v[36:39], v[158:161], v[182:185], v[36:39]
	v_mfma_f32_16x16x32_bf16 v[32:35], v[166:169], v[182:185], v[32:35]
	v_mfma_f32_16x16x32_bf16 v[20:23], v[158:161], v[190:193], v[20:23]
	v_mfma_f32_16x16x32_bf16 v[16:19], v[166:169], v[190:193], v[16:19]
	v_mfma_f32_16x16x32_bf16 v[4:7], v[158:161], v[198:201], v[4:7]
	v_mfma_f32_16x16x32_bf16 v[0:3], v[166:169], v[198:201], v[0:3]
	v_mfma_f32_16x16x32_bf16 v[52:55], v[162:165], v[178:181], v[52:55]
	v_mfma_f32_16x16x32_bf16 v[48:51], v[170:173], v[178:181], v[48:51]
	v_mfma_f32_16x16x32_bf16 v[36:39], v[162:165], v[186:189], v[36:39]
	v_mfma_f32_16x16x32_bf16 v[32:35], v[170:173], v[186:189], v[32:35]
	v_mfma_f32_16x16x32_bf16 v[20:23], v[162:165], v[194:197], v[20:23]
	v_mfma_f32_16x16x32_bf16 v[16:19], v[170:173], v[194:197], v[16:19]
	v_mfma_f32_16x16x32_bf16 v[4:7], v[162:165], v[202:205], v[4:7]
	v_mfma_f32_16x16x32_bf16 v[0:3], v[170:173], v[202:205], v[0:3]
	s_barrier
	s_addk_i32 s44, 0x200
	s_add_u32 s76, s76, 0x100
	s_addc_u32 s77, s77, 0
	s_add_i32 s22, s82, 2
	v_lshl_add_u64 v[136:137], v[136:137], 0, s[58:59]
	s_cmp_gt_u32 s82, 29
	v_lshl_add_u64 v[134:135], v[134:135], 0, s[58:59]
	s_cbranch_scc1 .LBB0_1261
	s_mov_b32 s82, s22
	s_branch .LBB0_1257
